# GLA chunk_out: 16 chunk-state loads issued before counted waits feed the MFMAs (was load-wait-mfma per load); padding keeps later code offsets
# baseline (speedup 1.0000x reference)
; template <bool IS_ML>
; __device__ __forceinline__ void chunk_out(LAS unsigned char* lds, unsigned char* ws, const float* w1, const float* w2, const float* onorm, int bid, int nb, int wid_s) {
;     ...
;       if (tid < 64) { const float mp = ((const float*)(ws + WS_SMALL + SM_MST))[c * 4 + h]; const float bt = GM(0)[tid]; const float inter = bt + mp;
;         float mx = -1e30f; for (int s = 0; s <= tid; ++s) mx = fmaxf(mx, GM(1)[s] - GM(0)[s]);
;         const float mt = fmaxf(inter, mx + bt); GM(2)[tid] = mt; GM(4)[tid] = __expf(inter - mt); GM(3)[tid] = 0.f; }
.LBB0_143:
	s_or_b64 exec, exec, s[36:37]
	s_waitcnt lgkmcnt(0)
	s_barrier
	s_and_saveexec_b64 s[54:55], s[0:1]
	s_cbranch_execz .LBB0_155
	s_ashr_i32 s89, s88, 31
	s_lshl_b64 s[30:31], s[88:89], 2
	v_readlane_b32 s36, v254, 48
	s_add_u32 s30, s36, s30
	v_readlane_b32 s36, v254, 45
	s_addc_u32 s31, s36, s31
	global_load_dword v5, v1, s[30:31]
	ds_read_b32 v4, v135
	ds_read_b32 v7, v135 offset:256
	s_mov_b64 s[68:69], exec
	s_waitcnt lgkmcnt(0)
	v_sub_f32_e32 v6, v7, v4
	s_nop 1
	v_max_f32_dpp v6, v6, v6 row_shr:1 row_mask:0xf bank_mask:0xf
	s_nop 1
	v_max_f32_dpp v6, v6, v6 row_shr:2 row_mask:0xf bank_mask:0xf
	s_nop 1
	v_max_f32_dpp v6, v6, v6 row_shr:4 row_mask:0xf bank_mask:0xf
	s_nop 1
	v_max_f32_dpp v6, v6, v6 row_shr:8 row_mask:0xf bank_mask:0xf
	s_nop 1
	v_max_f32_dpp v6, v6, v6 row_bcast:15 row_mask:0xa bank_mask:0xf
	s_nop 1
	v_max_f32_dpp v6, v6, v6 row_bcast:31 row_mask:0xc bank_mask:0xf
	s_nop 1
	v_max_f32_e32 v6, 0xf149f2ca, v6
	s_branch .LBB0_154
	s_nop 0
	s_nop 0
	s_nop 0
	s_nop 0
	s_nop 0
	s_nop 0
	s_nop 0
	s_nop 0
	s_nop 0
	s_nop 0
	s_nop 0
	s_nop 0
	s_nop 0
	s_nop 0
	s_nop 0
	s_nop 0
	s_nop 0
	s_nop 0
	s_nop 0
	s_nop 0
	s_nop 0
	s_nop 0
	s_nop 0
	s_nop 0
	s_nop 0
	s_nop 0
	s_nop 0
	s_nop 0
	s_nop 0
	s_nop 0
	s_nop 0
	s_nop 0
	s_nop 0
	s_nop 0
	s_nop 0
	s_nop 0
	s_nop 0
	s_nop 0
	s_nop 0
	s_nop 0
	s_nop 0
	s_nop 0
	s_nop 0
	s_nop 0
	s_nop 0
	s_nop 0
	s_nop 0
	s_nop 0
	s_nop 0
	s_nop 0
	s_nop 0
	s_nop 0
	s_nop 0
	s_nop 0
	s_nop 0
	s_nop 0
	s_nop 0
	s_nop 0
	s_nop 0
	s_nop 0
	s_nop 0
	s_nop 0
	s_nop 0
	s_nop 0
	s_nop 0
	s_nop 0
	s_nop 0
	s_nop 0
	s_nop 0
	s_nop 0
	s_nop 0
	s_nop 0
	s_nop 0
	s_nop 0
	s_nop 0
	s_nop 0
	s_nop 0
	s_nop 0
.LBB0_154:
	s_or_b64 exec, exec, s[68:69]
	s_waitcnt vmcnt(0) lgkmcnt(0)
	v_add_f32_e32 v5, v5, v4
	v_add_f32_e32 v4, v4, v6
	v_max_f32_e32 v4, v5, v4
	v_sub_f32_e32 v5, v5, v4
	v_mul_f32_e32 v5, 0x3fb8aa3b, v5
	v_exp_f32_e32 v5, v5
	ds_write_b32 v136, v4
	ds_write_b32 v137, v5
	ds_write_b32 v138, v1

; __device__ __forceinline__ f32x4 mfma16(bf16x8 a, bf16x8 b, f32x4 c) { return __builtin_amdgcn_mfma_f32_16x16x32_bf16(a, b, c, 0, 0, 0); }
; template <bool IS_ML>
; __device__ __forceinline__ void chunk_out(LAS unsigned char* lds, unsigned char* ws, const float* w1, const float* w2, const float* onorm, int bid, int nb, int wid_s) {
;     ...
;       for (int ks = 0; ks < 4; ++ks) { const bf16x8 a = LDSV8(C_QD + ((tt * 16 + fr) * 136 + ks * 32 + kg * 8) * 2);
; #pragma unroll
;         for (int j = 0; j < 8; ++j) { const bf16x8 bv = *(const bf16x8*)(BS + ((size_t)(c * 4 + h) * 256 + (vb + j) * 16 + fr) * 128 + ks * 32 + kg * 8);
;           if (IS_ML) acc2[j] = mfma16(a, bv, acc2[j]); else acc[j] = mfma16(a, bv, acc[j]); } }
.LBB0_211:
	v_lshl_add_u64 v[60:61], v[68:69], 0, s[26:27]
	v_add_u32_e32 v73, v120, v0
	v_add_u32_e32 v0, 0x80, v0
	ds_read_b128 v[52:55], v73 offset:33792
	ds_read_b128 v[56:59], v73 offset:33856
	s_mov_b64 s[100:101], 0x9e00000
	v_lshl_add_u64 v[50:51], v[60:61], 0, s[100:101]
	s_mov_b64 s[100:101], 0x9e01000
	v_lshl_add_u64 v[48:49], v[60:61], 0, s[100:101]
	s_mov_b64 s[100:101], 0x9e02000
	v_lshl_add_u64 v[46:47], v[60:61], 0, s[100:101]
	s_mov_b64 s[100:101], 0x9e03000
	v_lshl_add_u64 v[44:45], v[60:61], 0, s[100:101]
	s_mov_b64 s[100:101], 0x9e04000
	v_lshl_add_u64 v[42:43], v[60:61], 0, s[100:101]
	s_mov_b64 s[100:101], 0x9e05000
	v_lshl_add_u64 v[40:41], v[60:61], 0, s[100:101]
	s_mov_b64 s[100:101], 0x9e06000
	v_lshl_add_u64 v[38:39], v[60:61], 0, s[100:101]
	v_lshl_add_u64 v[228:229], v[70:71], 0, s[26:27]
	s_mov_b64 s[100:101], 0x9e00000
	s_nop 0
	v_lshl_add_u64 v[228:229], v[228:229], 0, s[100:101]
	global_load_dwordx4 v[144:147], v[50:51], off
	global_load_dwordx4 v[148:151], v[48:49], off
	global_load_dwordx4 v[152:155], v[46:47], off
	global_load_dwordx4 v[156:159], v[44:45], off
	global_load_dwordx4 v[160:163], v[42:43], off
	global_load_dwordx4 v[164:167], v[40:41], off
	global_load_dwordx4 v[180:183], v[38:39], off
	global_load_dwordx4 v[184:187], v[228:229], off
	global_load_dwordx4 v[188:191], v[50:51], off offset:64
	global_load_dwordx4 v[192:195], v[48:49], off offset:64
	global_load_dwordx4 v[196:199], v[46:47], off offset:64
	global_load_dwordx4 v[200:203], v[44:45], off offset:64
	global_load_dwordx4 v[212:215], v[42:43], off offset:64
	global_load_dwordx4 v[216:219], v[40:41], off offset:64
	global_load_dwordx4 v[220:223], v[38:39], off offset:64
	global_load_dwordx4 v[224:227], v[228:229], off offset:64
	s_add_u32 s26, s26, 0x80
	s_addc_u32 s27, s27, 0
	s_waitcnt lgkmcnt(0)
	s_waitcnt vmcnt(15)
	v_mfma_f32_16x16x32_bf16 v[18:21], v[52:55], v[144:147], v[18:21]
	s_waitcnt vmcnt(14)
	v_mfma_f32_16x16x32_bf16 v[30:33], v[52:55], v[148:151], v[30:33]
	s_waitcnt vmcnt(13)
	v_mfma_f32_16x16x32_bf16 v[34:37], v[52:55], v[152:155], v[34:37]
	s_waitcnt vmcnt(12)
	v_mfma_f32_16x16x32_bf16 v[22:25], v[52:55], v[156:159], v[22:25]
	s_waitcnt vmcnt(11)
	v_mfma_f32_16x16x32_bf16 v[14:17], v[52:55], v[160:163], v[14:17]
	s_waitcnt vmcnt(10)
	v_mfma_f32_16x16x32_bf16 v[10:13], v[52:55], v[164:167], v[10:13]
	s_waitcnt vmcnt(9)
	v_mfma_f32_16x16x32_bf16 v[6:9], v[52:55], v[180:183], v[6:9]
	s_waitcnt vmcnt(8)
	v_mfma_f32_16x16x32_bf16 v[26:29], v[52:55], v[184:187], v[26:29]
	s_waitcnt vmcnt(7)
	v_mfma_f32_16x16x32_bf16 v[18:21], v[56:59], v[188:191], v[18:21]
	s_waitcnt vmcnt(6)
	v_mfma_f32_16x16x32_bf16 v[30:33], v[56:59], v[192:195], v[30:33]
	s_waitcnt vmcnt(5)
	v_mfma_f32_16x16x32_bf16 v[34:37], v[56:59], v[196:199], v[34:37]
	s_waitcnt vmcnt(4)
	v_mfma_f32_16x16x32_bf16 v[22:25], v[56:59], v[200:203], v[22:25]
	s_waitcnt vmcnt(3)
	v_mfma_f32_16x16x32_bf16 v[14:17], v[56:59], v[212:215], v[14:17]
	s_waitcnt vmcnt(2)
	v_mfma_f32_16x16x32_bf16 v[10:13], v[56:59], v[216:219], v[10:13]
	s_waitcnt vmcnt(1)
	v_mfma_f32_16x16x32_bf16 v[6:9], v[56:59], v[220:223], v[6:9]
	s_waitcnt vmcnt(0)
	v_mfma_f32_16x16x32_bf16 v[26:29], v[56:59], v[224:227], v[26:29]
	s_cmpk_eq_i32 s26, 0x100
	s_cbranch_scc0 .LBB0_211
	s_barrier
	ds_write_b32 v126, v18
	ds_write_b32 v127, v30
	ds_write_b32 v128, v34
	ds_write_b32 v129, v22
	ds_write_b32 v130, v14
	ds_write_b32 v131, v10
	ds_write_b32 v132, v6
	ds_write_b32 v133, v26
	ds_write_b32 v126, v19 offset:1040
	ds_write_b32 v127, v31 offset:1040
	ds_write_b32 v128, v35 offset:1040
	ds_write_b32 v129, v23 offset:1040
	ds_write_b32 v130, v15 offset:1040
	ds_write_b32 v131, v11 offset:1040
	ds_write_b32 v132, v7 offset:1040
	ds_write_b32 v133, v27 offset:1040
	ds_write_b32 v126, v20 offset:2080
	ds_write_b32 v127, v32 offset:2080
	ds_write_b32 v128, v36 offset:2080
	ds_write_b32 v129, v24 offset:2080
	ds_write_b32 v130, v16 offset:2080
	ds_write_b32 v131, v12 offset:2080
	ds_write_b32 v132, v8 offset:2080
	ds_write_b32 v133, v28 offset:2080
	ds_write_b32 v126, v21 offset:3120
	ds_write_b32 v127, v33 offset:3120
	ds_write_b32 v128, v37 offset:3120
	ds_write_b32 v129, v25 offset:3120
	ds_write_b32 v130, v17 offset:3120
	ds_write_b32 v131, v13 offset:3120
	ds_write_b32 v132, v9 offset:3120
	ds_write_b32 v133, v29 offset:3120
	s_waitcnt lgkmcnt(0)
	s_barrier
; #define LAS __attribute__((address_space(3)))
; template <int MASK> __device__ __forceinline__ float sx(float v) { return __builtin_bit_cast(float, __builtin_amdgcn_ds_swizzle(__builtin_bit_cast(int, v), (MASK << 10) | 0x1f)); }
; __device__ __forceinline__ void unpack8(const u32x4 w, float (&o)[8]) { o[0] = bflo(w.x); o[1] = bfhi(w.x); o[2] = bflo(w.y); o[3] = bfhi(w.y); o[4] = bflo(w.z); o[5] = bfhi(w.z); o[6] = bflo(w.w); o[7] = bfhi(w.w); }
; template <bool IS_ML>
; __device__ __forceinline__ void chunk_out(LAS unsigned char* lds, unsigned char* ws, const float* w1, const float* w2, const float* onorm, int bid, int nb, int wid_s) {
;     ...
;     { const int t = tid >> 3, part = tid & 7, v0 = part * 32;
;       float dn = 1.f;
;       if (IS_ML) { const float den = GM(3)[t] + GM(4)[t] * dinter; dn = 1.f / fmaxf(fabsf(den), __expf(-GM(2)[t])); }
;       float ov[32]; float ss = 0.f;
; #pragma unroll
;       for (int i = 0; i < 8; ++i) { const f32x4 o4 = *(const LAS f32x4*)(OO + t * 260 + v0 + 4 * i); ov[4 * i] = o4.x * dn; ov[4 * i + 1] = o4.y * dn; ov[4 * i + 2] = o4.z * dn; ov[4 * i + 3] = o4.w * dn; }
; #pragma unroll
;       for (int i = 0; i < 32; ++i) ss += ov[i] * ov[i];
;       ss += sx<1>(ss); ss += sx<2>(ss); ss += sx<4>(ss);
;       const float rs = 1.0f / sqrtf(ss * (1.f / 256.f) + 1e-6f);
;       const bf16_t* gp = P + (size_t)(c * 64 + t) * 3328 + 2048 + h * 256 + v0; bf16_t* op = AO + (size_t)(c * 64 + t) * 1024 + h * 256 + v0;
; #pragma unroll
;       for (int i = 0; i < 4; ++i) { float g8[8]; unpack8(*(const u32x4*)(gp + 8 * i), g8); const f32x4 n0 = *(const f32x4*)(onorm + h * 256 + v0 + 8 * i), n1 = *(const f32x4*)(onorm + h * 256 + v0 + 8 * i + 4);
	ds_read_b128 v[46:49], v92
	ds_read_b128 v[38:41], v92 offset:16
	ds_read_b128 v[34:37], v92 offset:32
	ds_read_b128 v[26:29], v92 offset:48
	ds_read_b128 v[22:25], v92 offset:64
	ds_read_b128 v[14:17], v92 offset:80
	ds_read_b128 v[10:13], v92 offset:96
	ds_read_b128 v[6:9], v92 offset:112
	s_waitcnt lgkmcnt(7)
	v_mul_f32_e32 v0, v47, v47
	v_fmac_f32_e32 v0, v46, v46
	v_fmac_f32_e32 v0, v48, v48
	v_fmac_f32_e32 v0, v49, v49
	s_waitcnt lgkmcnt(6)
	v_fmac_f32_e32 v0, v38, v38
	v_fmac_f32_e32 v0, v39, v39
	v_fmac_f32_e32 v0, v40, v40
	v_fmac_f32_e32 v0, v41, v41
	s_waitcnt lgkmcnt(5)
	v_fmac_f32_e32 v0, v34, v34
	v_fmac_f32_e32 v0, v35, v35
	v_fmac_f32_e32 v0, v36, v36
	v_fmac_f32_e32 v0, v37, v37
	s_waitcnt lgkmcnt(4)
	v_fmac_f32_e32 v0, v26, v26
	v_fmac_f32_e32 v0, v27, v27
	v_fmac_f32_e32 v0, v28, v28
	v_fmac_f32_e32 v0, v29, v29
	s_waitcnt lgkmcnt(3)
	v_fmac_f32_e32 v0, v22, v22
	v_fmac_f32_e32 v0, v23, v23
	v_fmac_f32_e32 v0, v24, v24
	v_fmac_f32_e32 v0, v25, v25
	s_waitcnt lgkmcnt(2)
	v_fmac_f32_e32 v0, v14, v14
	v_fmac_f32_e32 v0, v15, v15
	v_fmac_f32_e32 v0, v16, v16
	v_fmac_f32_e32 v0, v17, v17
	s_waitcnt lgkmcnt(1)
	v_fmac_f32_e32 v0, v10, v10
	v_fmac_f32_e32 v0, v11, v11
	v_fmac_f32_e32 v0, v12, v12
	v_fmac_f32_e32 v0, v13, v13
	s_waitcnt lgkmcnt(0)
	v_pk_mul_f32 v[20:21], v[6:7], v[6:7]
	v_pk_mul_f32 v[18:19], v[8:9], v[8:9]
	v_add_f32_e32 v0, v20, v0
	v_add_f32_e32 v0, v21, v0
	v_add_f32_e32 v0, v18, v0
	v_add_f32_e32 v0, v19, v0
	ds_swizzle_b32 v18, v0 offset:swizzle(SWAP,1)
	s_lshl_b32 s58, s33, 1
	v_mov_b32_e32 v75, v1
	s_add_i32 s28, s28, s46
	v_lshl_add_u64 v[68:69], v[68:69], 0, s[34:35]
	s_waitcnt lgkmcnt(0)
	v_add_f32_e32 v0, v0, v18
	ds_swizzle_b32 v18, v0 offset:swizzle(SWAP,2)
	v_lshl_add_u64 v[70:71], v[70:71], 0, s[34:35]
	s_waitcnt lgkmcnt(0)
	v_add_f32_e32 v0, v0, v18
	ds_swizzle_b32 v18, v0 offset:swizzle(SWAP,4)
	s_waitcnt lgkmcnt(0)
	v_add_f32_e32 v0, v0, v18
	v_fmamk_f32 v0, v0, 0x3b800000, v205
	v_cmp_gt_f32_e32 vcc, s42, v0
	v_mul_f32_e32 v18, 0x4f800000, v0
	s_nop 0
	v_cndmask_b32_e32 v0, v0, v18, vcc
	v_sqrt_f32_e32 v18, v0
	s_nop 0
	v_add_u32_e32 v19, -1, v18
	v_fma_f32 v20, -v19, v18, v0
	v_cmp_ge_f32_e64 s[26:27], 0, v20
	v_add_u32_e32 v20, 1, v18
	s_nop 0
	v_cndmask_b32_e64 v19, v18, v19, s[26:27]
	v_fma_f32 v18, -v20, v18, v0
	v_cmp_lt_f32_e64 s[26:27], 0, v18
	s_nop 1
	v_cndmask_b32_e64 v18, v19, v20, s[26:27]
	v_mul_f32_e32 v19, 0x37800000, v18
	v_cndmask_b32_e32 v18, v18, v19, vcc
	v_cmp_class_f32_e32 vcc, v0, v206
	s_nop 1
	v_cndmask_b32_e32 v0, v18, v0, vcc
	v_div_scale_f32 v18, s[26:27], v0, v0, 1.0
	v_rcp_f32_e32 v19, v18
	s_movk_i32 s26, 0x1a00
	v_fma_f32 v20, -v18, v19, 1.0
	v_fmac_f32_e32 v19, v20, v19
	v_div_scale_f32 v20, vcc, 1.0, v0, 1.0
	v_mul_f32_e32 v21, v20, v19
	v_fma_f32 v30, -v18, v21, v20
	v_fmac_f32_e32 v21, v30, v19
	v_fma_f32 v18, -v18, v21, v20
	v_div_fmas_f32 v18, v18, v19, v21
	v_div_fixup_f32 v0, v18, v0, 1.0
	v_add_u32_e32 v18, s36, v91
	v_ashrrev_i32_e32 v19, 31, v18
	v_mov_b64_e32 v[20:21], s[54:55]
	v_mad_i64_i32 v[20:21], s[26:27], v18, s26, v[20:21]
	v_lshlrev_b64 v[18:19], 11, v[18:19]
	v_lshl_add_u64 v[20:21], v[20:21], 0, s[58:59]
	v_lshl_add_u64 v[18:19], s[30:31], 0, v[18:19]
	v_lshl_add_u64 v[20:21], v[20:21], 0, v[74:75]
	v_lshl_add_u64 v[18:19], v[18:19], 0, s[58:59]
	s_mov_b64 s[26:27], 0x1000
	v_lshl_add_u64 v[76:77], v[18:19], 0, v[74:75]
	v_add_co_u32_e32 v18, vcc, s52, v20
	v_lshl_add_u64 v[42:43], v[20:21], 0, s[26:27]
	s_lshl_b32 s58, s33, 2
	v_addc_co_u32_e32 v19, vcc, 0, v21, vcc
	v_lshl_add_u64 v[78:79], v[66:67], 0, s[58:59]
	global_load_dwordx4 v[54:57], v[18:19], off
	s_nop 0
	global_load_dwordx4 v[18:21], v[42:43], off offset:48
	global_load_dwordx4 v[30:33], v[42:43], off offset:32
	s_nop 0
	global_load_dwordx4 v[42:45], v[42:43], off offset:16
	s_nop 0
	global_load_dwordx4 v[50:53], v[78:79], off offset:16
	global_load_dwordx4 v[58:61], v[78:79], off
	s_cmpk_gt_i32 s28, 0x3ff
	s_waitcnt vmcnt(5)
	v_and_b32_e32 v138, 0xffff0000, v54
	v_lshlrev_b32_e32 v137, 16, v55
	v_lshlrev_b32_e32 v136, 16, v54
	v_and_b32_e32 v139, 0xffff0000, v55
	v_mul_f32_e32 v55, 0xbfb8aa3b, v138
	v_mul_f32_e32 v54, 0xbfb8aa3b, v136
	v_exp_f32_e32 v140, v55
	v_mul_f32_e32 v55, 0xbfb8aa3b, v137
	v_exp_f32_e32 v54, v54
	v_exp_f32_e32 v55, v55
	s_waitcnt vmcnt(0)
; __device__ __forceinline__ float sigm(float z) { return 1.f / (1.f + __expf(-z)); }
; __device__ __forceinline__ void unpack8(const u32x4 w, float (&o)[8]) { o[0] = bflo(w.x); o[1] = bfhi(w.x); o[2] = bflo(w.y); o[3] = bfhi(w.y); o[4] = bflo(w.z); o[5] = bfhi(w.z); o[6] = bflo(w.w); o[7] = bfhi(w.w); }
; __device__ __forceinline__ u32x4 pack8(const float (&o)[8]) { return (u32x4){pk2(o[0], o[1]), pk2(o[2], o[3]), pk2(o[4], o[5]), pk2(o[6], o[7])}; }
; template <bool IS_ML>
; __device__ __forceinline__ void chunk_out(LAS unsigned char* lds, unsigned char* ws, const float* w1, const float* w2, const float* onorm, int bid, int nb, int wid_s) {
;     ...
;       for (int i = 0; i < 4; ++i) { float g8[8]; unpack8(*(const u32x4*)(gp + 8 * i), g8); const f32x4 n0 = *(const f32x4*)(onorm + h * 256 + v0 + 8 * i), n1 = *(const f32x4*)(onorm + h * 256 + v0 + 8 * i + 4);
;         const float nn[8] = {n0.x, n0.y, n0.z, n0.w, n1.x, n1.y, n1.z, n1.w}; float o8[8];
; #pragma unroll
;         for (int e = 0; e < 8; ++e) { const float gz = g8[e]; const float gate = IS_ML ? sigm(gz) : gz * sigm(gz); o8[e] = ov[8 * i + e] * rs * nn[e] * gate; }
;         *(u32x4*)(op + 8 * i) = pack8(o8); }
	v_mov_b32_e32 v143, v60
	v_pk_add_f32 v[54:55], v[54:55], 1.0 op_sel_hi:[1,0]
	s_nop 0
	v_div_scale_f32 v73, s[26:27], v55, v55, 1.0
	v_rcp_f32_e32 v75, v73
	s_nop 0
	v_fma_f32 v135, -v73, v75, 1.0
	v_fmac_f32_e32 v75, v135, v75
	v_div_scale_f32 v135, vcc, 1.0, v55, 1.0
	v_mul_f32_e32 v141, v135, v75
	v_fma_f32 v142, -v73, v141, v135
	v_fmac_f32_e32 v141, v142, v75
	v_fma_f32 v73, -v73, v141, v135
	v_div_fmas_f32 v73, v73, v75, v141
	v_div_fixup_f32 v55, v73, v55, 1.0
	v_div_scale_f32 v73, s[26:27], v54, v54, 1.0
	v_rcp_f32_e32 v75, v73
	s_nop 0
	v_fma_f32 v135, -v73, v75, 1.0
	v_fmac_f32_e32 v75, v135, v75
	v_div_scale_f32 v135, vcc, 1.0, v54, 1.0
	v_mul_f32_e32 v141, v135, v75
	v_fma_f32 v142, -v73, v141, v135
	v_fmac_f32_e32 v141, v142, v75
	v_fma_f32 v73, -v73, v141, v135
	v_div_fmas_f32 v73, v73, v75, v141
	v_div_fixup_f32 v54, v73, v54, 1.0
	v_pk_mul_f32 v[54:55], v[54:55], v[136:137]
	v_mov_b32_e32 v136, v46
	v_mul_f32_e32 v46, 0xbfb8aa3b, v139
	v_exp_f32_e32 v141, v46
	v_mov_b32_e32 v137, v48
	v_pk_mul_f32 v[136:137], v[136:137], v[0:1] op_sel_hi:[1,0]
	v_mov_b32_e32 v142, v58
	v_pk_mul_f32 v[136:137], v[142:143], v[136:137]
	s_nop 0
	v_pk_mul_f32 v[54:55], v[54:55], v[136:137]
	v_pk_add_f32 v[136:137], v[140:141], 1.0 op_sel_hi:[1,0]
	s_nop 0
	v_div_scale_f32 v46, s[26:27], v137, v137, 1.0
	v_rcp_f32_e32 v48, v46
	s_nop 0
	v_fma_f32 v58, -v46, v48, 1.0
	v_fmac_f32_e32 v48, v58, v48
	v_div_scale_f32 v58, vcc, 1.0, v137, 1.0
	v_mul_f32_e32 v60, v58, v48
	v_fma_f32 v73, -v46, v60, v58
	v_fmac_f32_e32 v60, v73, v48
	v_fma_f32 v46, -v46, v60, v58
	v_div_fmas_f32 v46, v46, v48, v60
	v_div_fixup_f32 v137, v46, v137, 1.0
	v_div_scale_f32 v46, s[26:27], v136, v136, 1.0
	v_rcp_f32_e32 v48, v46
	s_nop 0
	v_fma_f32 v58, -v46, v48, 1.0
	v_fmac_f32_e32 v48, v58, v48
	v_div_scale_f32 v58, vcc, 1.0, v136, 1.0
	v_mul_f32_e32 v60, v58, v48
	v_fma_f32 v73, -v46, v60, v58
	v_fmac_f32_e32 v60, v73, v48
	v_fma_f32 v46, -v46, v60, v58
	v_div_fmas_f32 v46, v46, v48, v60
	v_mov_b32_e32 v48, v47
	v_div_fixup_f32 v136, v46, v136, 1.0
	v_pk_mul_f32 v[46:47], v[48:49], v[0:1] op_sel_hi:[1,0]
	v_lshlrev_b32_e32 v48, 16, v56
	v_and_b32_e32 v56, 0xffff0000, v56
	v_mov_b32_e32 v60, v59
	v_lshlrev_b32_e32 v49, 16, v57
	v_mul_f32_e32 v59, 0xbfb8aa3b, v56
	v_pk_mul_f32 v[46:47], v[60:61], v[46:47]
	v_mul_f32_e32 v58, 0xbfb8aa3b, v48
	v_exp_f32_e32 v60, v59
	v_mul_f32_e32 v59, 0xbfb8aa3b, v49
	v_exp_f32_e32 v58, v58
	v_exp_f32_e32 v59, v59
	v_pk_mul_f32 v[136:137], v[136:137], v[138:139]
	v_and_b32_e32 v57, 0xffff0000, v57
	v_pk_mul_f32 v[46:47], v[136:137], v[46:47]
	v_pk_add_f32 v[58:59], v[58:59], 1.0 op_sel_hi:[1,0]
	v_mov_b32_e32 v137, v52
	v_div_scale_f32 v61, s[26:27], v59, v59, 1.0
	v_rcp_f32_e32 v73, v61
	s_nop 0
	v_fma_f32 v75, -v61, v73, 1.0
	v_fmac_f32_e32 v73, v75, v73
	v_div_scale_f32 v75, vcc, 1.0, v59, 1.0
	v_mul_f32_e32 v135, v75, v73
	v_fma_f32 v136, -v61, v135, v75
	v_fmac_f32_e32 v135, v136, v73
	v_fma_f32 v61, -v61, v135, v75
	v_div_fmas_f32 v61, v61, v73, v135
	v_div_fixup_f32 v59, v61, v59, 1.0
	v_div_scale_f32 v61, s[26:27], v58, v58, 1.0
	v_rcp_f32_e32 v73, v61
	s_nop 0
	v_fma_f32 v75, -v61, v73, 1.0
	v_fmac_f32_e32 v73, v75, v73
	v_div_scale_f32 v75, vcc, 1.0, v58, 1.0
	v_mul_f32_e32 v135, v75, v73
	v_fma_f32 v136, -v61, v135, v75
	v_fmac_f32_e32 v135, v136, v73
	v_fma_f32 v61, -v61, v135, v75
	v_div_fmas_f32 v61, v61, v73, v135
	v_div_fixup_f32 v58, v61, v58, 1.0
	v_pk_mul_f32 v[48:49], v[58:59], v[48:49]
	v_mov_b32_e32 v58, v38
	v_mul_f32_e32 v38, 0xbfb8aa3b, v57
	v_exp_f32_e32 v61, v38
	v_mov_b32_e32 v59, v40
	v_pk_mul_f32 v[58:59], v[58:59], v[0:1] op_sel_hi:[1,0]
	v_mov_b32_e32 v136, v50
	v_pk_mul_f32 v[58:59], v[136:137], v[58:59]
	s_nop 0
	v_pk_mul_f32 v[48:49], v[48:49], v[58:59]
	v_pk_add_f32 v[58:59], v[60:61], 1.0 op_sel_hi:[1,0]
	s_nop 0
	v_div_scale_f32 v38, s[26:27], v59, v59, 1.0
	v_rcp_f32_e32 v40, v38
	s_nop 0
	v_fma_f32 v50, -v38, v40, 1.0
	v_fmac_f32_e32 v40, v50, v40
	v_div_scale_f32 v50, vcc, 1.0, v59, 1.0
	v_mul_f32_e32 v52, v50, v40
	v_fma_f32 v60, -v38, v52, v50
	v_fmac_f32_e32 v52, v60, v40
	v_fma_f32 v38, -v38, v52, v50
	v_div_fmas_f32 v38, v38, v40, v52
	v_div_fixup_f32 v59, v38, v59, 1.0
	v_div_scale_f32 v38, s[26:27], v58, v58, 1.0
	v_rcp_f32_e32 v40, v38
	s_nop 0
	v_fma_f32 v50, -v38, v40, 1.0
	v_fmac_f32_e32 v40, v50, v40
	v_div_scale_f32 v50, vcc, 1.0, v58, 1.0
	v_mul_f32_e32 v52, v50, v40
	v_fma_f32 v60, -v38, v52, v50
	v_fmac_f32_e32 v52, v60, v40
	v_fma_f32 v38, -v38, v52, v50
	v_div_fmas_f32 v38, v38, v40, v52
	v_mov_b32_e32 v40, v39
	v_div_fixup_f32 v58, v38, v58, 1.0
	v_pk_mul_f32 v[38:39], v[40:41], v[0:1] op_sel_hi:[1,0]
	v_mov_b32_e32 v52, v51
	v_pk_mul_f32 v[56:57], v[58:59], v[56:57]
	v_pk_mul_f32 v[38:39], v[52:53], v[38:39]
	v_bfe_u32 v50, v47, 16, 1
	v_pk_mul_f32 v[38:39], v[56:57], v[38:39]
	v_bfe_u32 v51, v46, 16, 1
	v_bfe_u32 v40, v39, 16, 1
	v_bfe_u32 v41, v38, 16, 1
	v_add3_u32 v46, v46, v51, s65
	v_add3_u32 v47, v47, v50, s65
	v_add3_u32 v38, v38, v41, s65
	v_add3_u32 v39, v39, v40, s65
	v_bfe_u32 v40, v54, 16, 1
	v_bfe_u32 v41, v55, 16, 1
	v_bfe_u32 v50, v48, 16, 1
	v_bfe_u32 v51, v49, 16, 1
	v_add3_u32 v49, v49, v51, s65
	v_add3_u32 v48, v48, v50, s65
	v_add3_u32 v41, v55, v41, s65
	v_add3_u32 v40, v54, v40, s65
	v_lshrrev_b32_e32 v50, 16, v40
	v_lshrrev_b32_e32 v51, 16, v41
	v_lshrrev_b32_e32 v40, 16, v48
	v_lshrrev_b32_e32 v41, 16, v49
	v_and_or_b32 v41, v39, s53, v41
	v_and_or_b32 v40, v38, s53, v40
	v_and_or_b32 v39, v47, s53, v51
	v_and_or_b32 v38, v46, s53, v50
	global_store_dwordx4 v[76:77], v[38:41], off
	global_load_dwordx4 v[38:41], v[78:79], off offset:48
	s_nop 0
	global_load_dwordx4 v[46:49], v[78:79], off offset:32
	v_and_b32_e32 v52, 0xffff0000, v42
	v_lshlrev_b32_e32 v51, 16, v43
	v_lshlrev_b32_e32 v50, 16, v42
	v_and_b32_e32 v53, 0xffff0000, v43
	v_mul_f32_e32 v43, 0xbfb8aa3b, v52
	v_mul_f32_e32 v42, 0xbfb8aa3b, v50
	v_exp_f32_e32 v54, v43
	v_mul_f32_e32 v43, 0xbfb8aa3b, v51
	v_exp_f32_e32 v42, v42
	v_exp_f32_e32 v43, v43
	s_nop 0
	v_pk_add_f32 v[42:43], v[42:43], 1.0 op_sel_hi:[1,0]
	s_nop 0
	v_div_scale_f32 v55, s[26:27], v43, v43, 1.0
	v_rcp_f32_e32 v56, v55
	s_nop 0
	v_fma_f32 v57, -v55, v56, 1.0
	v_fmac_f32_e32 v56, v57, v56
	v_div_scale_f32 v57, vcc, 1.0, v43, 1.0
	v_mul_f32_e32 v58, v57, v56
	v_fma_f32 v59, -v55, v58, v57
	v_fmac_f32_e32 v58, v59, v56
	v_fma_f32 v55, -v55, v58, v57
	v_div_fmas_f32 v55, v55, v56, v58
	v_div_fixup_f32 v43, v55, v43, 1.0
	v_div_scale_f32 v55, s[26:27], v42, v42, 1.0
	v_rcp_f32_e32 v56, v55
	s_nop 0
	v_fma_f32 v57, -v55, v56, 1.0
	v_fmac_f32_e32 v56, v57, v56
	v_div_scale_f32 v57, vcc, 1.0, v42, 1.0
	v_mul_f32_e32 v58, v57, v56
	v_fma_f32 v59, -v55, v58, v57
	v_fmac_f32_e32 v58, v59, v56
	v_fma_f32 v55, -v55, v58, v57
	v_div_fmas_f32 v55, v55, v56, v58
	v_div_fixup_f32 v42, v55, v42, 1.0
	v_pk_mul_f32 v[42:43], v[42:43], v[50:51]
	v_mov_b32_e32 v50, v34
	v_mul_f32_e32 v34, 0xbfb8aa3b, v53
	v_exp_f32_e32 v55, v34
	v_mov_b32_e32 v51, v36
	v_pk_mul_f32 v[50:51], v[50:51], v[0:1] op_sel_hi:[1,0]
	s_waitcnt vmcnt(0)
; __device__ __forceinline__ float sigm(float z) { return 1.f / (1.f + __expf(-z)); }
; __device__ __forceinline__ void unpack8(const u32x4 w, float (&o)[8]) { o[0] = bflo(w.x); o[1] = bfhi(w.x); o[2] = bflo(w.y); o[3] = bfhi(w.y); o[4] = bflo(w.z); o[5] = bfhi(w.z); o[6] = bflo(w.w); o[7] = bfhi(w.w); }
; __device__ __forceinline__ u32x4 pack8(const float (&o)[8]) { return (u32x4){pk2(o[0], o[1]), pk2(o[2], o[3]), pk2(o[4], o[5]), pk2(o[6], o[7])}; }
; template <bool IS_ML>
; __device__ __forceinline__ void chunk_out(LAS unsigned char* lds, unsigned char* ws, const float* w1, const float* w2, const float* onorm, int bid, int nb, int wid_s) {
;     ...
;       for (int i = 0; i < 4; ++i) { float g8[8]; unpack8(*(const u32x4*)(gp + 8 * i), g8); const f32x4 n0 = *(const f32x4*)(onorm + h * 256 + v0 + 8 * i), n1 = *(const f32x4*)(onorm + h * 256 + v0 + 8 * i + 4);
;         const float nn[8] = {n0.x, n0.y, n0.z, n0.w, n1.x, n1.y, n1.z, n1.w}; float o8[8];
; #pragma unroll
;         for (int e = 0; e < 8; ++e) { const float gz = g8[e]; const float gate = IS_ML ? sigm(gz) : gz * sigm(gz); o8[e] = ov[8 * i + e] * rs * nn[e] * gate; }
;         *(u32x4*)(op + 8 * i) = pack8(o8); }
	v_mov_b32_e32 v56, v46
	v_mov_b32_e32 v57, v48
	v_pk_mul_f32 v[50:51], v[56:57], v[50:51]
	s_nop 0
	v_pk_mul_f32 v[42:43], v[42:43], v[50:51]
	v_pk_add_f32 v[50:51], v[54:55], 1.0 op_sel_hi:[1,0]
	s_nop 0
	v_div_scale_f32 v34, s[26:27], v51, v51, 1.0
	v_rcp_f32_e32 v36, v34
	s_nop 0
	v_fma_f32 v46, -v34, v36, 1.0
	v_fmac_f32_e32 v36, v46, v36
	v_div_scale_f32 v46, vcc, 1.0, v51, 1.0
	v_mul_f32_e32 v48, v46, v36
	v_fma_f32 v54, -v34, v48, v46
	v_fmac_f32_e32 v48, v54, v36
	v_fma_f32 v34, -v34, v48, v46
	v_div_fmas_f32 v34, v34, v36, v48
	v_div_fixup_f32 v51, v34, v51, 1.0
	v_div_scale_f32 v34, s[26:27], v50, v50, 1.0
	v_rcp_f32_e32 v36, v34
	s_nop 0
	v_fma_f32 v46, -v34, v36, 1.0
	v_fmac_f32_e32 v36, v46, v36
	v_div_scale_f32 v46, vcc, 1.0, v50, 1.0
	v_mul_f32_e32 v48, v46, v36
	v_fma_f32 v54, -v34, v48, v46
	v_fmac_f32_e32 v48, v54, v36
	v_fma_f32 v34, -v34, v48, v46
	v_div_fmas_f32 v34, v34, v36, v48
	v_mov_b32_e32 v36, v35
	v_div_fixup_f32 v50, v34, v50, 1.0
	v_pk_mul_f32 v[34:35], v[36:37], v[0:1] op_sel_hi:[1,0]
	v_lshlrev_b32_e32 v36, 16, v44
	v_and_b32_e32 v44, 0xffff0000, v44
	v_mov_b32_e32 v48, v47
	v_lshlrev_b32_e32 v37, 16, v45
	v_mul_f32_e32 v47, 0xbfb8aa3b, v44
	v_pk_mul_f32 v[34:35], v[48:49], v[34:35]
	v_mul_f32_e32 v46, 0xbfb8aa3b, v36
	v_exp_f32_e32 v48, v47
	v_mul_f32_e32 v47, 0xbfb8aa3b, v37
	v_exp_f32_e32 v46, v46
	v_exp_f32_e32 v47, v47
	v_pk_mul_f32 v[50:51], v[50:51], v[52:53]
	v_and_b32_e32 v45, 0xffff0000, v45
	v_pk_mul_f32 v[34:35], v[50:51], v[34:35]
	v_pk_add_f32 v[46:47], v[46:47], 1.0 op_sel_hi:[1,0]
	s_nop 0
	v_div_scale_f32 v49, s[26:27], v47, v47, 1.0
	v_rcp_f32_e32 v50, v49
	s_nop 0
	v_fma_f32 v51, -v49, v50, 1.0
	v_fmac_f32_e32 v50, v51, v50
	v_div_scale_f32 v51, vcc, 1.0, v47, 1.0
	v_mul_f32_e32 v52, v51, v50
	v_fma_f32 v53, -v49, v52, v51
	v_fmac_f32_e32 v52, v53, v50
	v_fma_f32 v49, -v49, v52, v51
	v_div_fmas_f32 v49, v49, v50, v52
	v_div_fixup_f32 v47, v49, v47, 1.0
	v_div_scale_f32 v49, s[26:27], v46, v46, 1.0
	v_rcp_f32_e32 v50, v49
	s_nop 0
	v_fma_f32 v51, -v49, v50, 1.0
	v_fmac_f32_e32 v50, v51, v50
	v_div_scale_f32 v51, vcc, 1.0, v46, 1.0
	v_mul_f32_e32 v52, v51, v50
	v_fma_f32 v53, -v49, v52, v51
	v_fmac_f32_e32 v52, v53, v50
	v_fma_f32 v49, -v49, v52, v51
	v_div_fmas_f32 v49, v49, v50, v52
	v_div_fixup_f32 v46, v49, v46, 1.0
	v_pk_mul_f32 v[36:37], v[46:47], v[36:37]
	v_mov_b32_e32 v46, v26
	v_mul_f32_e32 v26, 0xbfb8aa3b, v45
	v_exp_f32_e32 v49, v26
	v_mov_b32_e32 v47, v28
	v_pk_mul_f32 v[46:47], v[46:47], v[0:1] op_sel_hi:[1,0]
	v_mov_b32_e32 v50, v38
	v_mov_b32_e32 v51, v40
	v_pk_mul_f32 v[46:47], v[50:51], v[46:47]
	s_nop 0
	v_pk_mul_f32 v[36:37], v[36:37], v[46:47]
	v_pk_add_f32 v[46:47], v[48:49], 1.0 op_sel_hi:[1,0]
	s_nop 0
	v_div_scale_f32 v26, s[26:27], v47, v47, 1.0
	v_rcp_f32_e32 v28, v26
	s_nop 0
	v_fma_f32 v38, -v26, v28, 1.0
	v_fmac_f32_e32 v28, v38, v28
	v_div_scale_f32 v38, vcc, 1.0, v47, 1.0
	v_mul_f32_e32 v40, v38, v28
	v_fma_f32 v48, -v26, v40, v38
	v_fmac_f32_e32 v40, v48, v28
	v_fma_f32 v26, -v26, v40, v38
	v_div_fmas_f32 v26, v26, v28, v40
	v_div_fixup_f32 v47, v26, v47, 1.0
	v_div_scale_f32 v26, s[26:27], v46, v46, 1.0
	v_rcp_f32_e32 v28, v26
	s_nop 0
	v_fma_f32 v38, -v26, v28, 1.0
	v_fmac_f32_e32 v28, v38, v28
	v_div_scale_f32 v38, vcc, 1.0, v46, 1.0
	v_mul_f32_e32 v40, v38, v28
	v_fma_f32 v48, -v26, v40, v38
	v_fmac_f32_e32 v40, v48, v28
	v_fma_f32 v26, -v26, v40, v38
	v_div_fmas_f32 v26, v26, v28, v40
	v_mov_b32_e32 v28, v27
	v_div_fixup_f32 v46, v26, v46, 1.0
	v_pk_mul_f32 v[26:27], v[28:29], v[0:1] op_sel_hi:[1,0]
	v_mov_b32_e32 v40, v39
	v_pk_mul_f32 v[44:45], v[46:47], v[44:45]
	v_pk_mul_f32 v[26:27], v[40:41], v[26:27]
	v_bfe_u32 v38, v35, 16, 1
	v_pk_mul_f32 v[26:27], v[44:45], v[26:27]
	v_bfe_u32 v39, v34, 16, 1
	v_bfe_u32 v28, v27, 16, 1
	v_bfe_u32 v29, v26, 16, 1
	v_add3_u32 v34, v34, v39, s65
	v_add3_u32 v35, v35, v38, s65
	v_add3_u32 v26, v26, v29, s65
	v_add3_u32 v27, v27, v28, s65
	v_bfe_u32 v28, v42, 16, 1
	v_bfe_u32 v29, v43, 16, 1
	v_bfe_u32 v38, v36, 16, 1
	v_bfe_u32 v39, v37, 16, 1
	v_add3_u32 v37, v37, v39, s65
	v_add3_u32 v36, v36, v38, s65
	v_add3_u32 v29, v43, v29, s65
	v_add3_u32 v28, v42, v28, s65
	v_lshrrev_b32_e32 v38, 16, v28
	v_lshrrev_b32_e32 v39, 16, v29
	v_lshrrev_b32_e32 v28, 16, v36
	v_lshrrev_b32_e32 v29, 16, v37
	v_and_or_b32 v29, v27, s53, v29
	v_and_or_b32 v28, v26, s53, v28
	v_and_or_b32 v27, v35, s53, v39
	v_and_or_b32 v26, v34, s53, v38
	global_store_dwordx4 v[76:77], v[26:29], off offset:16
	global_load_dwordx4 v[26:29], v[78:79], off offset:80
	s_nop 0
	global_load_dwordx4 v[34:37], v[78:79], off offset:64
	v_and_b32_e32 v40, 0xffff0000, v30
	v_lshlrev_b32_e32 v39, 16, v31
	v_lshlrev_b32_e32 v38, 16, v30
	v_and_b32_e32 v41, 0xffff0000, v31
	v_mul_f32_e32 v31, 0xbfb8aa3b, v40
	v_mul_f32_e32 v30, 0xbfb8aa3b, v38
	v_exp_f32_e32 v42, v31
	v_mul_f32_e32 v31, 0xbfb8aa3b, v39
	v_exp_f32_e32 v30, v30
	v_exp_f32_e32 v31, v31
	s_nop 0
	v_pk_add_f32 v[30:31], v[30:31], 1.0 op_sel_hi:[1,0]
	s_nop 0
	v_div_scale_f32 v43, s[26:27], v31, v31, 1.0
	v_rcp_f32_e32 v44, v43
	s_nop 0
	v_fma_f32 v45, -v43, v44, 1.0
	v_fmac_f32_e32 v44, v45, v44
	v_div_scale_f32 v45, vcc, 1.0, v31, 1.0
	v_mul_f32_e32 v46, v45, v44
	v_fma_f32 v47, -v43, v46, v45
	v_fmac_f32_e32 v46, v47, v44
	v_fma_f32 v43, -v43, v46, v45
	v_div_fmas_f32 v43, v43, v44, v46
	v_div_fixup_f32 v31, v43, v31, 1.0
	v_div_scale_f32 v43, s[26:27], v30, v30, 1.0
	v_rcp_f32_e32 v44, v43
	s_nop 0
	v_fma_f32 v45, -v43, v44, 1.0
	v_fmac_f32_e32 v44, v45, v44
	v_div_scale_f32 v45, vcc, 1.0, v30, 1.0
	v_mul_f32_e32 v46, v45, v44
	v_fma_f32 v47, -v43, v46, v45
	v_fmac_f32_e32 v46, v47, v44
	v_fma_f32 v43, -v43, v46, v45
	v_div_fmas_f32 v43, v43, v44, v46
	v_div_fixup_f32 v30, v43, v30, 1.0
	v_pk_mul_f32 v[30:31], v[30:31], v[38:39]
	v_mov_b32_e32 v38, v22
	v_mul_f32_e32 v22, 0xbfb8aa3b, v41
	v_exp_f32_e32 v43, v22
	v_mov_b32_e32 v39, v24
	v_pk_mul_f32 v[38:39], v[38:39], v[0:1] op_sel_hi:[1,0]
	s_waitcnt vmcnt(0)
; __device__ __forceinline__ float sigm(float z) { return 1.f / (1.f + __expf(-z)); }
; __device__ __forceinline__ void unpack8(const u32x4 w, float (&o)[8]) { o[0] = bflo(w.x); o[1] = bfhi(w.x); o[2] = bflo(w.y); o[3] = bfhi(w.y); o[4] = bflo(w.z); o[5] = bfhi(w.z); o[6] = bflo(w.w); o[7] = bfhi(w.w); }
; __device__ __forceinline__ u32x4 pack8(const float (&o)[8]) { return (u32x4){pk2(o[0], o[1]), pk2(o[2], o[3]), pk2(o[4], o[5]), pk2(o[6], o[7])}; }
; template <bool IS_ML>
; __device__ __forceinline__ void chunk_out(LAS unsigned char* lds, unsigned char* ws, const float* w1, const float* w2, const float* onorm, int bid, int nb, int wid_s) {
;     ...
;       for (int i = 0; i < 4; ++i) { float g8[8]; unpack8(*(const u32x4*)(gp + 8 * i), g8); const f32x4 n0 = *(const f32x4*)(onorm + h * 256 + v0 + 8 * i), n1 = *(const f32x4*)(onorm + h * 256 + v0 + 8 * i + 4);
;         const float nn[8] = {n0.x, n0.y, n0.z, n0.w, n1.x, n1.y, n1.z, n1.w}; float o8[8];
; #pragma unroll
;         for (int e = 0; e < 8; ++e) { const float gz = g8[e]; const float gate = IS_ML ? sigm(gz) : gz * sigm(gz); o8[e] = ov[8 * i + e] * rs * nn[e] * gate; }
;         *(u32x4*)(op + 8 * i) = pack8(o8); }
	v_mov_b32_e32 v44, v34
	v_mov_b32_e32 v45, v36
	v_pk_mul_f32 v[38:39], v[44:45], v[38:39]
	s_nop 0
	v_pk_mul_f32 v[30:31], v[30:31], v[38:39]
	v_pk_add_f32 v[38:39], v[42:43], 1.0 op_sel_hi:[1,0]
	s_nop 0
	v_div_scale_f32 v22, s[26:27], v39, v39, 1.0
	v_rcp_f32_e32 v24, v22
	s_nop 0
	v_fma_f32 v34, -v22, v24, 1.0
	v_fmac_f32_e32 v24, v34, v24
	v_div_scale_f32 v34, vcc, 1.0, v39, 1.0
	v_mul_f32_e32 v36, v34, v24
	v_fma_f32 v42, -v22, v36, v34
	v_fmac_f32_e32 v36, v42, v24
	v_fma_f32 v22, -v22, v36, v34
	v_div_fmas_f32 v22, v22, v24, v36
	v_div_fixup_f32 v39, v22, v39, 1.0
	v_div_scale_f32 v22, s[26:27], v38, v38, 1.0
	v_rcp_f32_e32 v24, v22
	s_nop 0
	v_fma_f32 v34, -v22, v24, 1.0
	v_fmac_f32_e32 v24, v34, v24
	v_div_scale_f32 v34, vcc, 1.0, v38, 1.0
	v_mul_f32_e32 v36, v34, v24
	v_fma_f32 v42, -v22, v36, v34
	v_fmac_f32_e32 v36, v42, v24
	v_fma_f32 v22, -v22, v36, v34
	v_div_fmas_f32 v22, v22, v24, v36
	v_mov_b32_e32 v24, v23
	v_div_fixup_f32 v38, v22, v38, 1.0
	v_pk_mul_f32 v[22:23], v[24:25], v[0:1] op_sel_hi:[1,0]
	v_lshlrev_b32_e32 v24, 16, v32
	v_and_b32_e32 v32, 0xffff0000, v32
	v_mov_b32_e32 v36, v35
	v_lshlrev_b32_e32 v25, 16, v33
	v_mul_f32_e32 v35, 0xbfb8aa3b, v32
	v_pk_mul_f32 v[22:23], v[36:37], v[22:23]
	v_mul_f32_e32 v34, 0xbfb8aa3b, v24
	v_exp_f32_e32 v36, v35
	v_mul_f32_e32 v35, 0xbfb8aa3b, v25
	v_exp_f32_e32 v34, v34
	v_exp_f32_e32 v35, v35
	v_pk_mul_f32 v[38:39], v[38:39], v[40:41]
	v_and_b32_e32 v33, 0xffff0000, v33
	v_pk_mul_f32 v[22:23], v[38:39], v[22:23]
	v_pk_add_f32 v[34:35], v[34:35], 1.0 op_sel_hi:[1,0]
	s_nop 0
	v_div_scale_f32 v37, s[26:27], v35, v35, 1.0
	v_rcp_f32_e32 v38, v37
	s_nop 0
	v_fma_f32 v39, -v37, v38, 1.0
	v_fmac_f32_e32 v38, v39, v38
	v_div_scale_f32 v39, vcc, 1.0, v35, 1.0
	v_mul_f32_e32 v40, v39, v38
	v_fma_f32 v41, -v37, v40, v39
	v_fmac_f32_e32 v40, v41, v38
	v_fma_f32 v37, -v37, v40, v39
	v_div_fmas_f32 v37, v37, v38, v40
	v_div_fixup_f32 v35, v37, v35, 1.0
	v_div_scale_f32 v37, s[26:27], v34, v34, 1.0
	v_rcp_f32_e32 v38, v37
	s_nop 0
	v_fma_f32 v39, -v37, v38, 1.0
	v_fmac_f32_e32 v38, v39, v38
	v_div_scale_f32 v39, vcc, 1.0, v34, 1.0
	v_mul_f32_e32 v40, v39, v38
	v_fma_f32 v41, -v37, v40, v39
	v_fmac_f32_e32 v40, v41, v38
	v_fma_f32 v37, -v37, v40, v39
	v_div_fmas_f32 v37, v37, v38, v40
	v_div_fixup_f32 v34, v37, v34, 1.0
	v_pk_mul_f32 v[24:25], v[34:35], v[24:25]
	v_mov_b32_e32 v34, v14
	v_mul_f32_e32 v14, 0xbfb8aa3b, v33
	v_exp_f32_e32 v37, v14
	v_mov_b32_e32 v35, v16
	v_pk_mul_f32 v[34:35], v[34:35], v[0:1] op_sel_hi:[1,0]
	v_mov_b32_e32 v38, v26
	v_mov_b32_e32 v39, v28
	v_pk_mul_f32 v[34:35], v[38:39], v[34:35]
	s_nop 0
	v_pk_mul_f32 v[24:25], v[24:25], v[34:35]
	v_pk_add_f32 v[34:35], v[36:37], 1.0 op_sel_hi:[1,0]
	s_nop 0
	v_div_scale_f32 v14, s[26:27], v35, v35, 1.0
	v_rcp_f32_e32 v16, v14
	s_nop 0
	v_fma_f32 v26, -v14, v16, 1.0
	v_fmac_f32_e32 v16, v26, v16
	v_div_scale_f32 v26, vcc, 1.0, v35, 1.0
	v_mul_f32_e32 v28, v26, v16
	v_fma_f32 v36, -v14, v28, v26
	v_fmac_f32_e32 v28, v36, v16
	v_fma_f32 v14, -v14, v28, v26
	v_div_fmas_f32 v14, v14, v16, v28
	v_div_fixup_f32 v35, v14, v35, 1.0
	v_div_scale_f32 v14, s[26:27], v34, v34, 1.0
	v_rcp_f32_e32 v16, v14
	s_nop 0
	v_fma_f32 v26, -v14, v16, 1.0
	v_fmac_f32_e32 v16, v26, v16
	v_div_scale_f32 v26, vcc, 1.0, v34, 1.0
	v_mul_f32_e32 v28, v26, v16
	v_fma_f32 v36, -v14, v28, v26
	v_fmac_f32_e32 v28, v36, v16
	v_fma_f32 v14, -v14, v28, v26
	v_div_fmas_f32 v14, v14, v16, v28
	v_mov_b32_e32 v16, v15
	v_div_fixup_f32 v34, v14, v34, 1.0
	v_pk_mul_f32 v[14:15], v[16:17], v[0:1] op_sel_hi:[1,0]
	v_mov_b32_e32 v28, v27
	v_pk_mul_f32 v[32:33], v[34:35], v[32:33]
	v_pk_mul_f32 v[14:15], v[28:29], v[14:15]
	v_bfe_u32 v26, v23, 16, 1
	v_pk_mul_f32 v[14:15], v[32:33], v[14:15]
	v_bfe_u32 v27, v22, 16, 1
	v_bfe_u32 v16, v15, 16, 1
	v_bfe_u32 v17, v14, 16, 1
	v_add3_u32 v22, v22, v27, s65
	v_add3_u32 v23, v23, v26, s65
	v_add3_u32 v14, v14, v17, s65
	v_add3_u32 v15, v15, v16, s65
	v_bfe_u32 v16, v30, 16, 1
	v_bfe_u32 v17, v31, 16, 1
	v_bfe_u32 v26, v24, 16, 1
	v_bfe_u32 v27, v25, 16, 1
	v_add3_u32 v25, v25, v27, s65
	v_add3_u32 v24, v24, v26, s65
	v_add3_u32 v17, v31, v17, s65
	v_add3_u32 v16, v30, v16, s65
	v_lshrrev_b32_e32 v26, 16, v16
	v_lshrrev_b32_e32 v27, 16, v17
	v_lshrrev_b32_e32 v16, 16, v24
	v_lshrrev_b32_e32 v17, 16, v25
	v_and_or_b32 v17, v15, s53, v17
	v_and_or_b32 v16, v14, s53, v16
	v_and_or_b32 v15, v23, s53, v27
	v_and_or_b32 v14, v22, s53, v26
	global_store_dwordx4 v[76:77], v[14:17], off offset:32
	global_load_dwordx4 v[14:17], v[78:79], off offset:112
	s_nop 0
	global_load_dwordx4 v[22:25], v[78:79], off offset:96
	v_and_b32_e32 v28, 0xffff0000, v18
	v_lshlrev_b32_e32 v27, 16, v19
	v_lshlrev_b32_e32 v26, 16, v18
	v_and_b32_e32 v29, 0xffff0000, v19
	v_mul_f32_e32 v19, 0xbfb8aa3b, v28
	v_mul_f32_e32 v18, 0xbfb8aa3b, v26
	v_exp_f32_e32 v30, v19
	v_mul_f32_e32 v19, 0xbfb8aa3b, v27
	v_exp_f32_e32 v18, v18
	v_exp_f32_e32 v19, v19
	s_nop 0
	v_pk_add_f32 v[18:19], v[18:19], 1.0 op_sel_hi:[1,0]
	s_nop 0
	v_div_scale_f32 v31, s[26:27], v19, v19, 1.0
	v_rcp_f32_e32 v32, v31
	s_nop 0
	v_fma_f32 v33, -v31, v32, 1.0
	v_fmac_f32_e32 v32, v33, v32
	v_div_scale_f32 v33, vcc, 1.0, v19, 1.0
	v_mul_f32_e32 v34, v33, v32
	v_fma_f32 v35, -v31, v34, v33
	v_fmac_f32_e32 v34, v35, v32
	v_fma_f32 v31, -v31, v34, v33
	v_div_fmas_f32 v31, v31, v32, v34
	v_div_fixup_f32 v19, v31, v19, 1.0
	v_div_scale_f32 v31, s[26:27], v18, v18, 1.0
	v_rcp_f32_e32 v32, v31
	s_nop 0
	v_fma_f32 v33, -v31, v32, 1.0
	v_fmac_f32_e32 v32, v33, v32
	v_div_scale_f32 v33, vcc, 1.0, v18, 1.0
	v_mul_f32_e32 v34, v33, v32
	v_fma_f32 v35, -v31, v34, v33
	v_fmac_f32_e32 v34, v35, v32
	v_fma_f32 v31, -v31, v34, v33
	v_div_fmas_f32 v31, v31, v32, v34
	v_div_fixup_f32 v18, v31, v18, 1.0
	v_pk_mul_f32 v[18:19], v[18:19], v[26:27]
	v_mov_b32_e32 v26, v10
	v_mul_f32_e32 v10, 0xbfb8aa3b, v29
	v_exp_f32_e32 v31, v10
	v_mov_b32_e32 v27, v12
	v_pk_mul_f32 v[26:27], v[26:27], v[0:1] op_sel_hi:[1,0]
	s_waitcnt vmcnt(0)
; __device__ __forceinline__ float sigm(float z) { return 1.f / (1.f + __expf(-z)); }
; __device__ __forceinline__ void unpack8(const u32x4 w, float (&o)[8]) { o[0] = bflo(w.x); o[1] = bfhi(w.x); o[2] = bflo(w.y); o[3] = bfhi(w.y); o[4] = bflo(w.z); o[5] = bfhi(w.z); o[6] = bflo(w.w); o[7] = bfhi(w.w); }
; __device__ __forceinline__ u32x4 pack8(const float (&o)[8]) { return (u32x4){pk2(o[0], o[1]), pk2(o[2], o[3]), pk2(o[4], o[5]), pk2(o[6], o[7])}; }
; template <bool IS_ML>
; __device__ __forceinline__ void chunk_out(LAS unsigned char* lds, unsigned char* ws, const float* w1, const float* w2, const float* onorm, int bid, int nb, int wid_s) {
;     ...
;       const bf16_t* gp = P + (size_t)(c * 64 + t) * 3328 + 2048 + h * 256 + v0; bf16_t* op = AO + (size_t)(c * 64 + t) * 1024 + h * 256 + v0;
; #pragma unroll
;       for (int i = 0; i < 4; ++i) { float g8[8]; unpack8(*(const u32x4*)(gp + 8 * i), g8); const f32x4 n0 = *(const f32x4*)(onorm + h * 256 + v0 + 8 * i), n1 = *(const f32x4*)(onorm + h * 256 + v0 + 8 * i + 4);
;         const float nn[8] = {n0.x, n0.y, n0.z, n0.w, n1.x, n1.y, n1.z, n1.w}; float o8[8];
; #pragma unroll
;         for (int e = 0; e < 8; ++e) { const float gz = g8[e]; const float gate = IS_ML ? sigm(gz) : gz * sigm(gz); o8[e] = ov[8 * i + e] * rs * nn[e] * gate; }
;         *(u32x4*)(op + 8 * i) = pack8(o8); }
;     }
;     __syncthreads();
	v_mov_b32_e32 v32, v22
	v_mov_b32_e32 v33, v24
	v_pk_mul_f32 v[26:27], v[32:33], v[26:27]
	s_nop 0
	v_pk_mul_f32 v[18:19], v[18:19], v[26:27]
	v_pk_add_f32 v[26:27], v[30:31], 1.0 op_sel_hi:[1,0]
	s_nop 0
	v_div_scale_f32 v10, s[26:27], v27, v27, 1.0
	v_rcp_f32_e32 v12, v10
	s_nop 0
	v_fma_f32 v22, -v10, v12, 1.0
	v_fmac_f32_e32 v12, v22, v12
	v_div_scale_f32 v22, vcc, 1.0, v27, 1.0
	v_mul_f32_e32 v24, v22, v12
	v_fma_f32 v30, -v10, v24, v22
	v_fmac_f32_e32 v24, v30, v12
	v_fma_f32 v10, -v10, v24, v22
	v_div_fmas_f32 v10, v10, v12, v24
	v_div_fixup_f32 v27, v10, v27, 1.0
	v_div_scale_f32 v10, s[26:27], v26, v26, 1.0
	v_rcp_f32_e32 v12, v10
	s_nop 0
	v_fma_f32 v22, -v10, v12, 1.0
	v_fmac_f32_e32 v12, v22, v12
	v_div_scale_f32 v22, vcc, 1.0, v26, 1.0
	v_mul_f32_e32 v24, v22, v12
	v_fma_f32 v30, -v10, v24, v22
	v_fmac_f32_e32 v24, v30, v12
	v_fma_f32 v10, -v10, v24, v22
	v_div_fmas_f32 v10, v10, v12, v24
	v_mov_b32_e32 v12, v11
	v_div_fixup_f32 v26, v10, v26, 1.0
	v_pk_mul_f32 v[10:11], v[12:13], v[0:1] op_sel_hi:[1,0]
	v_lshlrev_b32_e32 v12, 16, v20
	v_and_b32_e32 v20, 0xffff0000, v20
	v_mov_b32_e32 v24, v23
	v_lshlrev_b32_e32 v13, 16, v21
	v_mul_f32_e32 v23, 0xbfb8aa3b, v20
	v_pk_mul_f32 v[10:11], v[24:25], v[10:11]
	v_mul_f32_e32 v22, 0xbfb8aa3b, v12
	v_exp_f32_e32 v24, v23
	v_mul_f32_e32 v23, 0xbfb8aa3b, v13
	v_exp_f32_e32 v22, v22
	v_exp_f32_e32 v23, v23
	v_pk_mul_f32 v[26:27], v[26:27], v[28:29]
	v_and_b32_e32 v21, 0xffff0000, v21
	v_pk_mul_f32 v[10:11], v[26:27], v[10:11]
	v_pk_add_f32 v[22:23], v[22:23], 1.0 op_sel_hi:[1,0]
	s_nop 0
	v_div_scale_f32 v25, s[26:27], v23, v23, 1.0
	v_rcp_f32_e32 v26, v25
	s_nop 0
	v_fma_f32 v27, -v25, v26, 1.0
	v_fmac_f32_e32 v26, v27, v26
	v_div_scale_f32 v27, vcc, 1.0, v23, 1.0
	v_mul_f32_e32 v28, v27, v26
	v_fma_f32 v29, -v25, v28, v27
	v_fmac_f32_e32 v28, v29, v26
	v_fma_f32 v25, -v25, v28, v27
	v_div_fmas_f32 v25, v25, v26, v28
	v_div_fixup_f32 v23, v25, v23, 1.0
	v_div_scale_f32 v25, s[26:27], v22, v22, 1.0
	v_rcp_f32_e32 v26, v25
	s_nop 0
	v_fma_f32 v27, -v25, v26, 1.0
	v_fmac_f32_e32 v26, v27, v26
	v_div_scale_f32 v27, vcc, 1.0, v22, 1.0
	v_mul_f32_e32 v28, v27, v26
	v_fma_f32 v29, -v25, v28, v27
	v_fmac_f32_e32 v28, v29, v26
	v_fma_f32 v25, -v25, v28, v27
	v_div_fmas_f32 v25, v25, v26, v28
	v_div_fixup_f32 v22, v25, v22, 1.0
	v_pk_mul_f32 v[12:13], v[22:23], v[12:13]
	v_mov_b32_e32 v22, v6
	v_mul_f32_e32 v6, 0xbfb8aa3b, v21
	v_exp_f32_e32 v25, v6
	v_mov_b32_e32 v23, v8
	v_pk_mul_f32 v[22:23], v[22:23], v[0:1] op_sel_hi:[1,0]
	v_mov_b32_e32 v26, v14
	v_mov_b32_e32 v27, v16
	v_pk_mul_f32 v[22:23], v[26:27], v[22:23]
	s_nop 0
	v_pk_mul_f32 v[12:13], v[12:13], v[22:23]
	v_pk_add_f32 v[22:23], v[24:25], 1.0 op_sel_hi:[1,0]
	s_nop 0
	v_div_scale_f32 v6, s[26:27], v23, v23, 1.0
	v_rcp_f32_e32 v8, v6
	s_nop 0
	v_fma_f32 v14, -v6, v8, 1.0
	v_fmac_f32_e32 v8, v14, v8
	v_div_scale_f32 v14, vcc, 1.0, v23, 1.0
	v_mul_f32_e32 v16, v14, v8
	v_fma_f32 v24, -v6, v16, v14
	v_fmac_f32_e32 v16, v24, v8
	v_fma_f32 v6, -v6, v16, v14
	v_div_fmas_f32 v6, v6, v8, v16
	v_div_fixup_f32 v23, v6, v23, 1.0
	v_div_scale_f32 v6, s[26:27], v22, v22, 1.0
	v_rcp_f32_e32 v8, v6
	s_nop 0
	v_fma_f32 v14, -v6, v8, 1.0
	v_fmac_f32_e32 v8, v14, v8
	v_div_scale_f32 v14, vcc, 1.0, v22, 1.0
	v_mul_f32_e32 v16, v14, v8
	v_fma_f32 v24, -v6, v16, v14
	v_fmac_f32_e32 v16, v24, v8
	v_fma_f32 v6, -v6, v16, v14
	v_div_fmas_f32 v6, v6, v8, v16
	v_mov_b32_e32 v8, v7
	v_div_fixup_f32 v22, v6, v22, 1.0
	v_pk_mul_f32 v[6:7], v[8:9], v[0:1] op_sel_hi:[1,0]
	v_mov_b32_e32 v16, v15
	v_pk_mul_f32 v[20:21], v[22:23], v[20:21]
	v_pk_mul_f32 v[6:7], v[16:17], v[6:7]
	v_bfe_u32 v9, v11, 16, 1
	v_pk_mul_f32 v[6:7], v[20:21], v[6:7]
	v_bfe_u32 v14, v10, 16, 1
	v_bfe_u32 v0, v7, 16, 1
	v_bfe_u32 v8, v6, 16, 1
	v_add3_u32 v10, v10, v14, s65
	v_add3_u32 v11, v11, v9, s65
	v_add3_u32 v6, v6, v8, s65
	v_add3_u32 v0, v7, v0, s65
	v_bfe_u32 v7, v18, 16, 1
	v_bfe_u32 v8, v19, 16, 1
	v_bfe_u32 v9, v12, 16, 1
	v_bfe_u32 v14, v13, 16, 1
	v_add3_u32 v13, v13, v14, s65
	v_add3_u32 v9, v12, v9, s65
	v_add3_u32 v8, v19, v8, s65
	v_add3_u32 v7, v18, v7, s65
	v_lshrrev_b32_e32 v12, 16, v7
	v_lshrrev_b32_e32 v7, 16, v8
	v_lshrrev_b32_e32 v8, 16, v9
	v_lshrrev_b32_e32 v9, 16, v13
	v_and_or_b32 v9, v0, s53, v9
	v_and_or_b32 v8, v6, s53, v8
	v_and_or_b32 v7, v11, s53, v7
	v_and_or_b32 v6, v10, s53, v12
	global_store_dwordx4 v[76:77], v[6:9], off offset:48
	s_barrier
	s_cbranch_scc0 .LBB0_198
	s_mov_b32 s21, 0xf800000
	s_mov_b32 s36, s44
	s_mov_b32 s44, s46
